# P3: conv-unit workgroups stage the first two K-tiles of their retention unit in the conv unit's last K-iteration; the second GEMM call skips its prologue stage loads for them
# baseline (speedup 1.0000x reference)
; #define PG8_STAGE(bufoff, gbase, voff) do { _Pragma("unroll") for (int _i = 0; _i < 2; ++_i) \
;         __builtin_amdgcn_global_load_lds((const unsigned*)((const char*)(gbase) + (voff)[_i]), (PG8_LAS unsigned*)(lds + (bufoff) + ldsw + _i * 8192), 16, 0, 0); } while (0)
; #define PG8_LDA(dst, b, h) do { _Pragma("unroll") for (int m = 0; m < 4; ++m) _Pragma("unroll") for (int k = 0; k < 2; ++k) dst[m][k] = *(const PG8_LAS bf16x8*)(lds + PG8_SA(b, h) + aoff + m * 2048 + k * 1024); } while (0)
; #define PG8_LDB(dst, b, h) do { _Pragma("unroll") for (int n = 0; n < 2; ++n) _Pragma("unroll") for (int k = 0; k < 2; ++k) dst[n][k] = *(const PG8_LAS bf16x8*)(lds + PG8_SB(b, h) + boff + n * 2048 + k * 1024); } while (0)
; #define PG8_MMA(ai, bj, At, Bt) do { __builtin_amdgcn_s_setprio(1); _Pragma("unroll") for (int m = 0; m < 4; ++m) _Pragma("unroll") for (int n = 0; n < 2; ++n) _Pragma("unroll") for (int k = 0; k < 2; ++k) \
;         acc[ai][bj][m][n] = __builtin_amdgcn_mfma_f32_16x16x32_bf16(Bt[n][k], At[m][k], acc[ai][bj][m][n], 0, 0, 0); __builtin_amdgcn_s_setprio(0); } while (0)
; #define PG8_WAIT_V(n) asm volatile("s_waitcnt vmcnt(" #n ")" ::: "memory")
; #define PG8_BAR __builtin_amdgcn_s_barrier()
; template <class Epi, class Sched, bool ALIGN_EPI = false, bool SP2 = false>
; __device__ __forceinline__ void gemm_phase(PG8_LAS unsigned char* lds, const Gemm g, const Sched& S, const Epi& E) {
;     ...
;         for (int t = 0; t < nt; t += 2) {
;             const bool last = (t == nt - 2);
;             const char* a1 = cA + (size_t)(t + 1) * kstep;
;             const char* a2 = last ? nA : cA + (size_t)(t + 2) * kstep; const char* b2 = last ? nB : cB + (size_t)(t + 2) * kstep;
;             const char* a3 = a2 + kstep; const char* b3 = b2 + kstep;
;             if (last && has_next) S.a_ready(nxt);
;             if constexpr (SP2) {
;             PG8_LDB(B0, 0, 0); PG8_LDB(B1, 0, 1); PG8_SCHED; PG8_LDA(At, 0, 0); PG8_STAGE(PG8_SA(1, 1), a1 + hstep, voffA);
;             PG8_WAIT_V(8); PG8_WAIT_L(0); PG8_BAR; PG8_MMA(0, 0, At, B0); PG8_MMA(0, 1, At, B1); PG8_BAR; PG8_SCHED;
;             PG8_LDA(At, 0, 1); PG8_STAGE(PG8_SB(0, 0), b2, voffB); PG8_STAGE(PG8_SB(0, 1), b2 + hstep, voffB); PG8_STAGE(PG8_SA(0, 0), a2, voffA);
;             PG8_WAIT_V(8); PG8_WAIT_L(0); PG8_BAR; PG8_MMA(1, 0, At, B0); PG8_MMA(1, 1, At, B1); PG8_BAR; PG8_SCHED;
.LBB0_706:
	s_add_u32 s6, s4, 0xebb40080
	s_addc_u32 s7, s5, -1
	s_cmp_lg_u32 s21, 12
	s_cselect_b32 s6, s6, 0
	s_cselect_b32 s7, s7, 0
	s_add_u32 s8, s2, s6
	s_addc_u32 s9, s3, s7
	s_add_i32 s22, 0, 0x10000
	s_add_u32 s6, s0, s6
	s_addc_u32 s7, s1, s7
	s_cmp_lg_u32 s21, 12
	s_cbranch_scc1 .Lp3a_notlast
	s_add_u32 s8, s8, 0xf7600000
	s_addc_u32 s9, s9, -1
	s_add_u32 s6, s6, 0xffe00000
	s_addc_u32 s7, s7, -1
.Lp3a_notlast:
	s_add_i32 s24, 0, 0x14000
	v_add_u32_e32 v154, s22, v140
	v_add_u32_e32 v170, s24, v140
	ds_read_b128 v[142:145], v154
	ds_read_b128 v[146:149], v154 offset:1024
	ds_read_b128 v[150:153], v154 offset:2048
	ds_read_b128 v[154:157], v154 offset:3072
	ds_read_b128 v[158:161], v170
	ds_read_b128 v[162:165], v170 offset:1024
	ds_read_b128 v[166:169], v170 offset:2048
	ds_read_b128 v[170:173], v170 offset:3072
	v_lshl_add_u64 v[186:187], v[134:135], 0, s[4:5]
	s_add_i32 m0, s14, 0xc000
	ds_read_b128 v[174:177], v141
	ds_read_b128 v[178:181], v141 offset:1024
	ds_read_b128 v[182:185], v141 offset:2048
	ds_read_b128 v[194:197], v141 offset:3072
	ds_read_b128 v[198:201], v141 offset:4096
	ds_read_b128 v[202:205], v141 offset:5120
	ds_read_b128 v[210:213], v141 offset:6144
	ds_read_b128 v[214:217], v141 offset:7168
	global_load_lds_dwordx4 v[186:187], off
	v_lshl_add_u64 v[186:187], v[136:137], 0, s[4:5]
	s_add_i32 m0, s14, 0xe000
	s_nop 0
	global_load_lds_dwordx4 v[186:187], off
	s_waitcnt vmcnt(8)
	s_waitcnt lgkmcnt(0)
	s_barrier
	s_setprio 1
	s_waitcnt lgkmcnt(0)
	v_mfma_f32_16x16x32_bf16 v[124:127], v[142:145], v[174:177], v[124:127]
	v_mfma_f32_16x16x32_bf16 v[120:123], v[150:153], v[174:177], v[120:123]
	v_mfma_f32_16x16x32_bf16 v[108:111], v[142:145], v[182:185], v[108:111]
	v_mfma_f32_16x16x32_bf16 v[104:107], v[150:153], v[182:185], v[104:107]
	v_mfma_f32_16x16x32_bf16 v[92:95], v[142:145], v[198:201], v[92:95]
	v_mfma_f32_16x16x32_bf16 v[88:91], v[150:153], v[198:201], v[88:91]
	v_mfma_f32_16x16x32_bf16 v[76:79], v[142:145], v[210:213], v[76:79]
	v_mfma_f32_16x16x32_bf16 v[72:75], v[150:153], v[210:213], v[72:75]
	v_mfma_f32_16x16x32_bf16 v[124:127], v[146:149], v[178:181], v[124:127]
	v_mfma_f32_16x16x32_bf16 v[120:123], v[154:157], v[178:181], v[120:123]
	v_mfma_f32_16x16x32_bf16 v[108:111], v[146:149], v[194:197], v[108:111]
	v_mfma_f32_16x16x32_bf16 v[104:107], v[154:157], v[194:197], v[104:107]
	v_mfma_f32_16x16x32_bf16 v[92:95], v[146:149], v[202:205], v[92:95]
	v_mfma_f32_16x16x32_bf16 v[88:91], v[154:157], v[202:205], v[88:91]
	v_mfma_f32_16x16x32_bf16 v[76:79], v[146:149], v[214:217], v[76:79]
	v_mfma_f32_16x16x32_bf16 v[72:75], v[154:157], v[214:217], v[72:75]
	s_setprio 0
	s_setprio 1
	v_mfma_f32_16x16x32_bf16 v[116:119], v[158:161], v[174:177], v[116:119]
	v_mfma_f32_16x16x32_bf16 v[112:115], v[166:169], v[174:177], v[112:115]
	v_mfma_f32_16x16x32_bf16 v[100:103], v[158:161], v[182:185], v[100:103]
	v_mfma_f32_16x16x32_bf16 v[96:99], v[166:169], v[182:185], v[96:99]
	v_mfma_f32_16x16x32_bf16 v[84:87], v[158:161], v[198:201], v[84:87]
	v_mfma_f32_16x16x32_bf16 v[80:83], v[166:169], v[198:201], v[80:83]
	v_mfma_f32_16x16x32_bf16 v[68:71], v[158:161], v[210:213], v[68:71]
	v_mfma_f32_16x16x32_bf16 v[64:67], v[166:169], v[210:213], v[64:67]
	v_mfma_f32_16x16x32_bf16 v[116:119], v[162:165], v[178:181], v[116:119]
	v_mfma_f32_16x16x32_bf16 v[112:115], v[170:173], v[178:181], v[112:115]
	v_mfma_f32_16x16x32_bf16 v[100:103], v[162:165], v[194:197], v[100:103]
	v_mfma_f32_16x16x32_bf16 v[96:99], v[170:173], v[194:197], v[96:99]
	v_mfma_f32_16x16x32_bf16 v[84:87], v[162:165], v[202:205], v[84:87]
	v_mfma_f32_16x16x32_bf16 v[80:83], v[170:173], v[202:205], v[80:83]
	v_mfma_f32_16x16x32_bf16 v[68:71], v[162:165], v[214:217], v[68:71]
	v_mfma_f32_16x16x32_bf16 v[64:67], v[170:173], v[214:217], v[64:67]
	s_setprio 0
	s_barrier
	s_add_i32 s22, s22, s13
	v_lshl_add_u64 v[186:187], s[6:7], 0, v[188:189]
	s_mov_b32 m0, s22
	ds_read_b128 v[174:177], v141 offset:16384
	ds_read_b128 v[178:181], v141 offset:17408
	ds_read_b128 v[182:185], v141 offset:18432
	ds_read_b128 v[194:197], v141 offset:19456
	ds_read_b128 v[198:201], v141 offset:20480
	ds_read_b128 v[202:205], v141 offset:21504
	ds_read_b128 v[210:213], v141 offset:22528
	ds_read_b128 v[214:217], v141 offset:23552
	global_load_lds_dwordx4 v[186:187], off
	s_add_i32 m0, s22, 0x2000
	s_add_u32 s22, s6, 0x40000
	v_lshl_add_u64 v[190:191], s[6:7], 0, v[132:133]
	s_addc_u32 s23, s7, 0
	s_add_i32 s24, s24, s13
	global_load_lds_dwordx4 v[190:191], off
	v_lshl_add_u64 v[218:219], s[22:23], 0, v[188:189]
	s_mov_b32 m0, s24
	v_lshl_add_u64 v[220:221], s[8:9], 0, v[130:131]
	global_load_lds_dwordx4 v[218:219], off
	v_lshl_add_u64 v[218:219], s[22:23], 0, v[132:133]
	s_add_i32 m0, s24, 0x2000
	s_nop 0
	global_load_lds_dwordx4 v[218:219], off
	v_lshl_add_u64 v[218:219], s[8:9], 0, v[128:129]
	s_mov_b32 m0, s14
	s_nop 0
	global_load_lds_dwordx4 v[218:219], off
	s_mov_b32 m0, s15
	s_nop 0
	global_load_lds_dwordx4 v[220:221], off
	s_waitcnt vmcnt(8)
	s_waitcnt lgkmcnt(0)
	s_barrier
; #define PG8_STAGE(bufoff, gbase, voff) do { _Pragma("unroll") for (int _i = 0; _i < 2; ++_i) \
;         __builtin_amdgcn_global_load_lds((const unsigned*)((const char*)(gbase) + (voff)[_i]), (PG8_LAS unsigned*)(lds + (bufoff) + ldsw + _i * 8192), 16, 0, 0); } while (0)
; #define PG8_LDA(dst, b, h) do { _Pragma("unroll") for (int m = 0; m < 4; ++m) _Pragma("unroll") for (int k = 0; k < 2; ++k) dst[m][k] = *(const PG8_LAS bf16x8*)(lds + PG8_SA(b, h) + aoff + m * 2048 + k * 1024); } while (0)
; #define PG8_LDB(dst, b, h) do { _Pragma("unroll") for (int n = 0; n < 2; ++n) _Pragma("unroll") for (int k = 0; k < 2; ++k) dst[n][k] = *(const PG8_LAS bf16x8*)(lds + PG8_SB(b, h) + boff + n * 2048 + k * 1024); } while (0)
; #define PG8_MMA(ai, bj, At, Bt) do { __builtin_amdgcn_s_setprio(1); _Pragma("unroll") for (int m = 0; m < 4; ++m) _Pragma("unroll") for (int n = 0; n < 2; ++n) _Pragma("unroll") for (int k = 0; k < 2; ++k) \
;         acc[ai][bj][m][n] = __builtin_amdgcn_mfma_f32_16x16x32_bf16(Bt[n][k], At[m][k], acc[ai][bj][m][n], 0, 0, 0); __builtin_amdgcn_s_setprio(0); } while (0)
; #define PG8_WAIT_V(n) asm volatile("s_waitcnt vmcnt(" #n ")" ::: "memory")
; #define PG8_WAIT_L(n) asm volatile("s_waitcnt lgkmcnt(" #n ")" ::: "memory")
; #define PG8_BAR __builtin_amdgcn_s_barrier()
; #define PG8_SCHED __builtin_amdgcn_sched_barrier(0)
; template <class Epi, class Sched, bool ALIGN_EPI = false, bool SP2 = false>
; __device__ __forceinline__ void gemm_phase(PG8_LAS unsigned char* lds, const Gemm g, const Sched& S, const Epi& E) {
;     ...
;             PG8_WAIT_V(8); PG8_WAIT_L(0); PG8_BAR; PG8_MMA(1, 0, At, B0); PG8_MMA(1, 1, At, B1); PG8_BAR; PG8_SCHED;
;             PG8_LDB(B0, 1, 0); PG8_LDB(B1, 1, 1); PG8_SCHED; PG8_LDA(At, 1, 0); PG8_STAGE(PG8_SA(0, 1), a2 + hstep, voffA);
;             PG8_WAIT_V(8); PG8_WAIT_L(0); PG8_BAR; PG8_MMA(0, 0, At, B0); PG8_MMA(0, 1, At, B1); PG8_BAR; PG8_SCHED;
	s_setprio 1
	s_waitcnt lgkmcnt(0)
	v_mfma_f32_16x16x32_bf16 v[60:63], v[142:145], v[174:177], v[60:63]
	v_mfma_f32_16x16x32_bf16 v[56:59], v[150:153], v[174:177], v[56:59]
	v_mfma_f32_16x16x32_bf16 v[44:47], v[142:145], v[182:185], v[44:47]
	v_mfma_f32_16x16x32_bf16 v[40:43], v[150:153], v[182:185], v[40:43]
	v_mfma_f32_16x16x32_bf16 v[28:31], v[142:145], v[198:201], v[28:31]
	v_mfma_f32_16x16x32_bf16 v[24:27], v[150:153], v[198:201], v[24:27]
	v_mfma_f32_16x16x32_bf16 v[12:15], v[142:145], v[210:213], v[12:15]
	v_mfma_f32_16x16x32_bf16 v[8:11], v[150:153], v[210:213], v[8:11]
	v_mfma_f32_16x16x32_bf16 v[60:63], v[146:149], v[178:181], v[60:63]
	v_mfma_f32_16x16x32_bf16 v[56:59], v[154:157], v[178:181], v[56:59]
	v_mfma_f32_16x16x32_bf16 v[44:47], v[146:149], v[194:197], v[44:47]
	v_mfma_f32_16x16x32_bf16 v[40:43], v[154:157], v[194:197], v[40:43]
	v_mfma_f32_16x16x32_bf16 v[28:31], v[146:149], v[202:205], v[28:31]
	v_mfma_f32_16x16x32_bf16 v[24:27], v[154:157], v[202:205], v[24:27]
	v_mfma_f32_16x16x32_bf16 v[12:15], v[146:149], v[214:217], v[12:15]
	v_mfma_f32_16x16x32_bf16 v[8:11], v[154:157], v[214:217], v[8:11]
	s_setprio 0
	s_setprio 1
	v_mfma_f32_16x16x32_bf16 v[52:55], v[158:161], v[174:177], v[52:55]
	v_mfma_f32_16x16x32_bf16 v[48:51], v[166:169], v[174:177], v[48:51]
	v_mfma_f32_16x16x32_bf16 v[36:39], v[158:161], v[182:185], v[36:39]
	v_mfma_f32_16x16x32_bf16 v[32:35], v[166:169], v[182:185], v[32:35]
	v_mfma_f32_16x16x32_bf16 v[20:23], v[158:161], v[198:201], v[20:23]
	v_mfma_f32_16x16x32_bf16 v[16:19], v[166:169], v[198:201], v[16:19]
	v_mfma_f32_16x16x32_bf16 v[4:7], v[158:161], v[210:213], v[4:7]
	v_mfma_f32_16x16x32_bf16 v[0:3], v[166:169], v[210:213], v[0:3]
	v_mfma_f32_16x16x32_bf16 v[52:55], v[162:165], v[178:181], v[52:55]
	v_mfma_f32_16x16x32_bf16 v[48:51], v[170:173], v[178:181], v[48:51]
	v_mfma_f32_16x16x32_bf16 v[36:39], v[162:165], v[194:197], v[36:39]
	v_mfma_f32_16x16x32_bf16 v[32:35], v[170:173], v[194:197], v[32:35]
	v_mfma_f32_16x16x32_bf16 v[20:23], v[162:165], v[202:205], v[20:23]
	v_mfma_f32_16x16x32_bf16 v[16:19], v[170:173], v[202:205], v[16:19]
	v_mfma_f32_16x16x32_bf16 v[4:7], v[162:165], v[214:217], v[4:7]
	v_mfma_f32_16x16x32_bf16 v[0:3], v[170:173], v[214:217], v[0:3]
	s_setprio 0
	s_barrier
	s_add_i32 s22, 0, 0x18000
	s_add_i32 s23, 0, 0x1c000
	v_add_u32_e32 v154, s22, v140
	v_add_u32_e32 v170, s23, v140
	ds_read_b128 v[142:145], v154
	ds_read_b128 v[146:149], v154 offset:1024
	ds_read_b128 v[150:153], v154 offset:2048
	ds_read_b128 v[154:157], v154 offset:3072
	ds_read_b128 v[158:161], v170
	ds_read_b128 v[162:165], v170 offset:1024
	ds_read_b128 v[166:169], v170 offset:2048
	ds_read_b128 v[170:173], v170 offset:3072
	s_add_u32 s8, s8, 0x40000
	s_addc_u32 s9, s9, 0
	s_mov_b32 m0, s16
	v_lshl_add_u64 v[222:223], s[8:9], 0, v[128:129]
	ds_read_b128 v[174:177], v141 offset:32768
	ds_read_b128 v[178:181], v141 offset:33792
	ds_read_b128 v[182:185], v141 offset:34816
	ds_read_b128 v[194:197], v141 offset:35840
	ds_read_b128 v[198:201], v141 offset:36864
	ds_read_b128 v[202:205], v141 offset:37888
	ds_read_b128 v[210:213], v141 offset:38912
	ds_read_b128 v[214:217], v141 offset:39936
	global_load_lds_dwordx4 v[222:223], off
	v_lshl_add_u64 v[222:223], s[8:9], 0, v[130:131]
	s_mov_b32 m0, s17
	s_nop 0
	global_load_lds_dwordx4 v[222:223], off
	s_waitcnt vmcnt(8)
	s_waitcnt lgkmcnt(0)
	s_barrier
	s_setprio 1
	s_waitcnt lgkmcnt(0)
	v_mfma_f32_16x16x32_bf16 v[124:127], v[142:145], v[174:177], v[124:127]
	v_mfma_f32_16x16x32_bf16 v[120:123], v[150:153], v[174:177], v[120:123]
	v_mfma_f32_16x16x32_bf16 v[108:111], v[142:145], v[182:185], v[108:111]
	v_mfma_f32_16x16x32_bf16 v[104:107], v[150:153], v[182:185], v[104:107]
	v_mfma_f32_16x16x32_bf16 v[92:95], v[142:145], v[198:201], v[92:95]
	v_mfma_f32_16x16x32_bf16 v[88:91], v[150:153], v[198:201], v[88:91]
	v_mfma_f32_16x16x32_bf16 v[76:79], v[142:145], v[210:213], v[76:79]
	v_mfma_f32_16x16x32_bf16 v[72:75], v[150:153], v[210:213], v[72:75]
	v_mfma_f32_16x16x32_bf16 v[124:127], v[146:149], v[178:181], v[124:127]
	v_mfma_f32_16x16x32_bf16 v[120:123], v[154:157], v[178:181], v[120:123]
	v_mfma_f32_16x16x32_bf16 v[108:111], v[146:149], v[194:197], v[108:111]
	v_mfma_f32_16x16x32_bf16 v[104:107], v[154:157], v[194:197], v[104:107]
	v_mfma_f32_16x16x32_bf16 v[92:95], v[146:149], v[202:205], v[92:95]
	v_mfma_f32_16x16x32_bf16 v[88:91], v[154:157], v[202:205], v[88:91]
	v_mfma_f32_16x16x32_bf16 v[76:79], v[146:149], v[214:217], v[76:79]
	v_mfma_f32_16x16x32_bf16 v[72:75], v[154:157], v[214:217], v[72:75]
	s_setprio 0
	s_setprio 1
	v_mfma_f32_16x16x32_bf16 v[116:119], v[158:161], v[174:177], v[116:119]
	v_mfma_f32_16x16x32_bf16 v[112:115], v[166:169], v[174:177], v[112:115]
	v_mfma_f32_16x16x32_bf16 v[100:103], v[158:161], v[182:185], v[100:103]
	v_mfma_f32_16x16x32_bf16 v[96:99], v[166:169], v[182:185], v[96:99]
	v_mfma_f32_16x16x32_bf16 v[84:87], v[158:161], v[198:201], v[84:87]
	v_mfma_f32_16x16x32_bf16 v[80:83], v[166:169], v[198:201], v[80:83]
	v_mfma_f32_16x16x32_bf16 v[68:71], v[158:161], v[210:213], v[68:71]
	v_mfma_f32_16x16x32_bf16 v[64:67], v[166:169], v[210:213], v[64:67]
	v_mfma_f32_16x16x32_bf16 v[116:119], v[162:165], v[178:181], v[116:119]
	v_mfma_f32_16x16x32_bf16 v[112:115], v[170:173], v[178:181], v[112:115]
	v_mfma_f32_16x16x32_bf16 v[100:103], v[162:165], v[194:197], v[100:103]
	v_mfma_f32_16x16x32_bf16 v[96:99], v[170:173], v[194:197], v[96:99]
	v_mfma_f32_16x16x32_bf16 v[84:87], v[162:165], v[202:205], v[84:87]
	v_mfma_f32_16x16x32_bf16 v[80:83], v[170:173], v[202:205], v[80:83]
	v_mfma_f32_16x16x32_bf16 v[68:71], v[162:165], v[214:217], v[68:71]
	v_mfma_f32_16x16x32_bf16 v[64:67], v[170:173], v[214:217], v[64:67]
	s_setprio 0
	s_barrier
; #define PG8_STAGE(bufoff, gbase, voff) do { _Pragma("unroll") for (int _i = 0; _i < 2; ++_i) \
;         __builtin_amdgcn_global_load_lds((const unsigned*)((const char*)(gbase) + (voff)[_i]), (PG8_LAS unsigned*)(lds + (bufoff) + ldsw + _i * 8192), 16, 0, 0); } while (0)
; #define PG8_LDA(dst, b, h) do { _Pragma("unroll") for (int m = 0; m < 4; ++m) _Pragma("unroll") for (int k = 0; k < 2; ++k) dst[m][k] = *(const PG8_LAS bf16x8*)(lds + PG8_SA(b, h) + aoff + m * 2048 + k * 1024); } while (0)
; #define PG8_MMA(ai, bj, At, Bt) do { __builtin_amdgcn_s_setprio(1); _Pragma("unroll") for (int m = 0; m < 4; ++m) _Pragma("unroll") for (int n = 0; n < 2; ++n) _Pragma("unroll") for (int k = 0; k < 2; ++k) \
;         acc[ai][bj][m][n] = __builtin_amdgcn_mfma_f32_16x16x32_bf16(Bt[n][k], At[m][k], acc[ai][bj][m][n], 0, 0, 0); __builtin_amdgcn_s_setprio(0); } while (0)
; #define PG8_WAIT_V(n) asm volatile("s_waitcnt vmcnt(" #n ")" ::: "memory")
; #define PG8_WAIT_L(n) asm volatile("s_waitcnt lgkmcnt(" #n ")" ::: "memory")
; #define PG8_BAR __builtin_amdgcn_s_barrier()
; #define PG8_SCHED __builtin_amdgcn_sched_barrier(0)
;     __device__ __forceinline__ void operator()(const f32x4 (&acc)[2][2][4][2], const Unit& u, int wr, int wc, int fr, int fq) const {
;     ...
;             for (int m = 0; m < 4; ++m) { const size_t off = (size_t)(row0 + ai * HALF + m * 16) * 1024 + col0;
; #pragma unroll
;                 for (int bj = 0; bj < 2; ++bj) { const u32x4 gw = *(const u32x4*)(Gt + off + bj * HALF);
;                     f32x4 v0 = acc[ai][bj][m][0], v1 = acc[ai][bj][m][1];
;                     v0[0] *= bflo(gw.x); v0[1] *= bfhi(gw.x); v0[2] *= bflo(gw.y); v0[3] *= bfhi(gw.y);
;                     v1[0] *= bflo(gw.z); v1[1] *= bfhi(gw.z); v1[2] *= bflo(gw.w); v1[3] *= bfhi(gw.w);
; template <class Epi, class Sched, bool ALIGN_EPI = false, bool SP2 = false>
; __device__ __forceinline__ void gemm_phase(PG8_LAS unsigned char* lds, const Gemm g, const Sched& S, const Epi& E) {
;     ...
;             PG8_LDA(At, 1, 1); PG8_STAGE(PG8_SB(1, 0), b3, voffB); PG8_STAGE(PG8_SB(1, 1), b3 + hstep, voffB); PG8_STAGE(PG8_SA(1, 0), a3, voffA);
;             PG8_WAIT_V(8); PG8_WAIT_L(0); PG8_BAR; PG8_MMA(1, 0, At, B0); PG8_MMA(1, 1, At, B1); PG8_BAR; PG8_SCHED;
	s_add_i32 s8, s22, s13
	v_lshl_add_u64 v[186:187], v[186:187], 0, s[26:27]
	s_mov_b32 m0, s8
	ds_read_b128 v[174:177], v141 offset:49152
	ds_read_b128 v[178:181], v141 offset:50176
	ds_read_b128 v[182:185], v141 offset:51200
	ds_read_b128 v[194:197], v141 offset:52224
	ds_read_b128 v[198:201], v141 offset:53248
	ds_read_b128 v[202:205], v141 offset:54272
	ds_read_b128 v[210:213], v141 offset:55296
	ds_read_b128 v[214:217], v141 offset:56320
	global_load_lds_dwordx4 v[186:187], off
	s_add_i32 m0, s8, 0x2000
	s_add_u32 s6, s6, 0x40080
	v_lshl_add_u64 v[186:187], v[190:191], 0, s[26:27]
	s_addc_u32 s7, s7, 0
	s_add_i32 s8, s23, s13
	global_load_lds_dwordx4 v[186:187], off
	v_lshl_add_u64 v[186:187], s[6:7], 0, v[188:189]
	s_mov_b32 m0, s8
	s_nop 0
	global_load_lds_dwordx4 v[186:187], off
	v_lshl_add_u64 v[186:187], s[6:7], 0, v[132:133]
	s_add_i32 m0, s8, 0x2000
	s_nop 0
	global_load_lds_dwordx4 v[186:187], off
	v_lshl_add_u64 v[186:187], v[218:219], 0, s[26:27]
	s_mov_b32 m0, s19
	s_nop 0
	global_load_lds_dwordx4 v[186:187], off
	v_lshl_add_u64 v[186:187], v[220:221], 0, s[26:27]
	s_mov_b32 m0, s20
	s_nop 0
	global_load_lds_dwordx4 v[186:187], off
	s_waitcnt vmcnt(8)
	s_waitcnt lgkmcnt(0)
	s_barrier
	s_setprio 1
	s_waitcnt lgkmcnt(0)
	v_mfma_f32_16x16x32_bf16 v[60:63], v[142:145], v[174:177], v[60:63]
	v_mfma_f32_16x16x32_bf16 v[56:59], v[150:153], v[174:177], v[56:59]
	v_mfma_f32_16x16x32_bf16 v[44:47], v[142:145], v[182:185], v[44:47]
	v_mfma_f32_16x16x32_bf16 v[40:43], v[150:153], v[182:185], v[40:43]
	v_mfma_f32_16x16x32_bf16 v[28:31], v[142:145], v[198:201], v[28:31]
	v_mfma_f32_16x16x32_bf16 v[24:27], v[150:153], v[198:201], v[24:27]
	v_mfma_f32_16x16x32_bf16 v[12:15], v[142:145], v[210:213], v[12:15]
	v_mfma_f32_16x16x32_bf16 v[8:11], v[150:153], v[210:213], v[8:11]
	v_mfma_f32_16x16x32_bf16 v[60:63], v[146:149], v[178:181], v[60:63]
	v_mfma_f32_16x16x32_bf16 v[56:59], v[154:157], v[178:181], v[56:59]
	v_mfma_f32_16x16x32_bf16 v[44:47], v[146:149], v[194:197], v[44:47]
	v_mfma_f32_16x16x32_bf16 v[40:43], v[154:157], v[194:197], v[40:43]
	v_mfma_f32_16x16x32_bf16 v[28:31], v[146:149], v[202:205], v[28:31]
	v_mfma_f32_16x16x32_bf16 v[24:27], v[154:157], v[202:205], v[24:27]
	v_mfma_f32_16x16x32_bf16 v[12:15], v[146:149], v[214:217], v[12:15]
	v_mfma_f32_16x16x32_bf16 v[8:11], v[154:157], v[214:217], v[8:11]
	s_setprio 0
	s_setprio 1
	v_mfma_f32_16x16x32_bf16 v[52:55], v[158:161], v[174:177], v[52:55]
	v_mfma_f32_16x16x32_bf16 v[48:51], v[166:169], v[174:177], v[48:51]
	v_mfma_f32_16x16x32_bf16 v[36:39], v[158:161], v[182:185], v[36:39]
	v_mfma_f32_16x16x32_bf16 v[32:35], v[166:169], v[182:185], v[32:35]
	v_mfma_f32_16x16x32_bf16 v[20:23], v[158:161], v[198:201], v[20:23]
	v_mfma_f32_16x16x32_bf16 v[16:19], v[166:169], v[198:201], v[16:19]
	v_mfma_f32_16x16x32_bf16 v[4:7], v[158:161], v[210:213], v[4:7]
	v_mfma_f32_16x16x32_bf16 v[0:3], v[166:169], v[210:213], v[0:3]
	v_mfma_f32_16x16x32_bf16 v[52:55], v[162:165], v[178:181], v[52:55]
	v_mfma_f32_16x16x32_bf16 v[48:51], v[170:173], v[178:181], v[48:51]
	v_mfma_f32_16x16x32_bf16 v[36:39], v[162:165], v[194:197], v[36:39]
	v_mfma_f32_16x16x32_bf16 v[32:35], v[170:173], v[194:197], v[32:35]
	v_mfma_f32_16x16x32_bf16 v[20:23], v[162:165], v[202:205], v[20:23]
	v_mfma_f32_16x16x32_bf16 v[16:19], v[170:173], v[202:205], v[16:19]
	v_mfma_f32_16x16x32_bf16 v[4:7], v[162:165], v[214:217], v[4:7]
	v_mfma_f32_16x16x32_bf16 v[0:3], v[170:173], v[214:217], v[0:3]
	s_setprio 0
	s_barrier
	s_add_i32 s21, s21, 2
	s_add_u32 s4, s4, 0x100
	s_addc_u32 s5, s5, 0
	s_cmp_gt_u32 s21, 13
	s_cbranch_scc0 .LBB0_706
	v_lshl_add_u32 v128, s11, 8, v138
	v_or_b32_e32 v129, s18, v139
	v_lshlrev_b32_e32 v128, 11, v128
	v_lshl_add_u32 v128, v129, 1, v128
	s_lshl_b32 s4, s12, 9
	v_add_u32_e32 v128, s4, v128
	v_readlane_b32 s2, v254, 42
	v_readlane_b32 s3, v254, 43
	v_readlane_b32 s0, v254, 21
	v_readlane_b32 s1, v254, 22
	s_mov_b64 s[4:5], s[2:3]
	global_load_dwordx4 v[142:145], v128, s[4:5]
	global_load_dwordx4 v[146:149], v128, s[4:5] offset:256
	s_add_u32 s4, s2, 0x8000
	s_addc_u32 s5, s3, 0
	global_load_dwordx4 v[150:153], v128, s[4:5]
	global_load_dwordx4 v[154:157], v128, s[4:5] offset:256
	s_add_u32 s4, s2, 0x10000
	s_addc_u32 s5, s3, 0
	global_load_dwordx4 v[158:161], v128, s[4:5]
	global_load_dwordx4 v[162:165], v128, s[4:5] offset:256
	s_add_u32 s4, s2, 0x18000
	s_addc_u32 s5, s3, 0
	global_load_dwordx4 v[166:169], v128, s[4:5]
	global_load_dwordx4 v[170:173], v128, s[4:5] offset:256
	s_add_u32 s4, s2, 0x40000
	s_addc_u32 s5, s3, 0
	global_load_dwordx4 v[174:177], v128, s[4:5]
	global_load_dwordx4 v[178:181], v128, s[4:5] offset:256
	s_add_u32 s4, s2, 0x48000
	s_addc_u32 s5, s3, 0
	global_load_dwordx4 v[182:185], v128, s[4:5]
	global_load_dwordx4 v[194:197], v128, s[4:5] offset:256
	s_add_u32 s4, s2, 0x50000
	s_addc_u32 s5, s3, 0
	global_load_dwordx4 v[198:201], v128, s[4:5]
	global_load_dwordx4 v[202:205], v128, s[4:5] offset:256
	s_add_u32 s4, s2, 0x58000
	s_addc_u32 s5, s3, 0
	global_load_dwordx4 v[210:213], v128, s[4:5]
	global_load_dwordx4 v[214:217], v128, s[4:5] offset:256
	s_cmpk_lt_u32 s10, 0x100
	s_cbranch_scc0 .LBB0_709
	s_barrier

;     __host__ __device__ void init(int M, int N, int K, long L_) { base.init(M, N, 1, 0, K); L = L_; }
;     __host__ __device__ void init(int M0, int Mtot, int N, int K, int G_, int c_) { base.init(M0, N, G_, c_, K); nrest = ((Mtot - M0) / BM) * NN * S; nkp = (K / BK) / S; G = G_; c = c_; }
; __device__ __forceinline__ int bxl() { int b = blockIdx.x; asm volatile("" : "+s"(b)); return b; }
;     __host__ __device__ bool map(long L, Unit& u) const {
;         const bool ok = L < nwg; if (!ok) L = 0;
;         u.kt0 = 0; u.nkt = nktf;
;         int wgid = (int)L; { const int q = nwg / NXCD, r = nwg % NXCD, xcd = wgid % NXCD, off = wgid / NXCD; wgid = (xcd < r ? xcd * (q + 1) : r * (q + 1) + (xcd - r) * q) + off; }
;         const int nig = WGM * nN, gid = wgid / nig, fm = gid * WGM, gsz = (nM - fm) < WGM ? (nM - fm) : WGM;
;         u.pm = fm + ((wgid % nig) % gsz); u.pn = (wgid % nig) / gsz; return ok;
; __global__ void __launch_bounds__(NTHREADS, 2) fwd_megakernel(Args a_) {
;     ...
;             pg8::StaticOrder S; S.init(MP, DM, G, bxl(), DM);
;             { pg8::Gemm g{P  , (const bf16*)(wl + W_RET), MP, DM, DM}; pg8::EpiGate<true> E{MG, P + 6 * BS};
;               pg8::gemm_phase<pg8::EpiGate<true>, pg8::StaticOrder, true, true>(lds, g, S, E); }
.LBB0_710:
	v_readlane_b32 s24, v254, 8
	s_sub_u32 s60, s24, 20
	s_cmp_lt_u32 s60, 84
	s_cselect_b64 s[60:61], 0, -1
	s_cmpk_lt_i32 s24, 0x114
	s_cselect_b64 s[0:1], -1, 0
	s_and_b64 s[2:3], s[0:1], exec
	s_cselect_b32 s2, s24, 0
	s_ashr_i32 s3, s2, 31
	s_lshr_b32 s3, s3, 29
	s_add_i32 s5, s2, s3
	s_and_b32 s3, s5, -8
	v_mov_b32_e32 v11, v193
	s_sub_i32 s7, s2, s3
	v_mov_b32_e32 v135, v189
	v_readfirstlane_b32 s4, v11
	s_cmp_gt_i32 s7, 3
	s_mov_b64 s[2:3], -1
	s_cbranch_scc0 .LBB0_713
	s_mul_i32 s2, s7, 34
	s_add_i32 s6, s2, 4
	s_cbranch_execz .LBB0_714

; #define PG8_STAGE(bufoff, gbase, voff) do { _Pragma("unroll") for (int _i = 0; _i < 2; ++_i) \
;         __builtin_amdgcn_global_load_lds((const unsigned*)((const char*)(gbase) + (voff)[_i]), (PG8_LAS unsigned*)(lds + (bufoff) + ldsw + _i * 8192), 16, 0, 0); } while (0)
; #define PG8_WAIT_V(n) asm volatile("s_waitcnt vmcnt(" #n ")" ::: "memory")
; #define PG8_BAR __builtin_amdgcn_s_barrier()
; template <class Epi, class Sched, bool ALIGN_EPI = false, bool SP2 = false>
; __device__ __forceinline__ void gemm_phase(PG8_LAS unsigned char* lds, const Gemm g, const Sched& S, const Epi& E) {
;     ...
;     const int tid = tid_, wid = __builtin_amdgcn_readfirstlane(tid >> 6), lane = tid & 63, wr = wid >> 2, wc = wid & 3, fr = lane & 15, fq = lane >> 4;
;     const int K = g.K;
;     unsigned voffA[2], voffB[2];
; #pragma unroll
;     for (int i = 0; i < 2; ++i) { int R, C; stage_rc(tid * 16 + i * 8192, R, C); const int Rb = Epi::PERM ? ((R & ~31) + perm32(R & 31)) : R;
;         voffA[i] = (unsigned)(R * K + C) * 2u; voffB[i] = (unsigned)(Rb * K + C) * 2u; }
;     ...
;     const char* cA = (const char*)g.A + (size_t)cur.pm * tstep + (size_t)cur.kt0 * kstep; const char* cB = (const char*)g.Bt + (size_t)cur.pn * tstep + (size_t)cur.kt0 * kstep;
;     S.a_ready(cur);
;     if constexpr (SP2) {
;         PG8_STAGE(PG8_SB(0, 0), cB, voffB); PG8_STAGE(PG8_SB(0, 1), cB + hstep, voffB); PG8_STAGE(PG8_SA(0, 0), cA, voffA); PG8_STAGE(PG8_SA(0, 1), cA + hstep, voffA);
;         if (wr == 1) PG8_BAR;
;         PG8_WAIT_V(2); PG8_BAR;
;         PG8_STAGE(PG8_SB(1, 0), cB + kstep, voffB); PG8_STAGE(PG8_SA(1, 0), cA + kstep, voffA); PG8_STAGE(PG8_SB(1, 1), cB + hstep + kstep, voffB);
;         PG8_WAIT_V(6); PG8_BAR;
.LBB0_715:
	s_ashr_i32 s0, s5, 3
	s_add_i32 s0, s6, s0
	s_ashr_i32 s1, s0, 31
	s_lshr_b32 s1, s1, 27
	s_add_i32 s1, s0, s1
	s_ashr_i32 s2, s1, 5
	s_lshl_b32 s3, s2, 3
	s_sub_i32 s2, 0x45, s3
	s_min_u32 s5, s2, 8
	s_andn2_b32 s1, s1, 31
	s_sub_i32 s6, s0, s1
	v_cvt_f32_ubyte0_e32 v1, s5
	v_cvt_f32_i32_e32 v0, s6
	v_rcp_iflag_f32_e32 v2, v1
	s_ashr_i32 s0, s6, 30
	s_or_b32 s2, s0, 1
	v_mov_b32_e32 v6, 1
	v_mul_f32_e32 v2, v0, v2
	v_trunc_f32_e32 v2, v2
	v_fma_f32 v0, -v2, v1, v0
	v_cmp_ge_f32_e64 s[0:1], |v0|, v1
	v_ashrrev_i32_e32 v1, 31, v11
	v_lshrrev_b32_e32 v1, 26, v1
	v_add_u32_e32 v1, v11, v1
	v_ashrrev_i32_e32 v8, 6, v1
	v_bfe_i32 v1, v11, 27, 1
	v_cvt_i32_f32_e32 v2, v2
	v_lshlrev_b32_e32 v0, 4, v11
	v_lshrrev_b32_e32 v1, 22, v1
	v_add_u32_e32 v1, v0, v1
	v_and_b32_e32 v1, 0xfffffc00, v1
	s_and_b64 s[0:1], s[0:1], exec
	v_sub_u32_e32 v1, v0, v1
	v_readfirstlane_b32 s1, v2
	v_lshrrev_b32_e32 v2, 4, v1
	s_cselect_b32 s0, s2, 0
	v_bitop3_b32 v1, v2, v1, 32 bitop3:0x6c
	s_add_i32 s2, s1, s0
	v_ashrrev_i32_e32 v3, 31, v1
	s_mul_i32 s0, s2, s5
	v_lshrrev_b32_e32 v3, 26, v3
	s_sub_i32 s0, s6, s0
	v_add_u32_e32 v3, v1, v3
	s_sext_i32_i8 s0, s0
	v_lshlrev_b32_e32 v2, 3, v8
	v_ashrrev_i32_e32 v9, 6, v3
	v_and_b32_e32 v3, 0xc0, v3
	s_add_i32 s14, s3, s0
	v_readlane_b32 s0, v255, 9
	v_and_b32_e32 v2, -16, v2
	v_sub_u32_e32 v1, v1, v3
	s_add_u32 s25, s0, 0x1200000
	v_readlane_b32 s0, v255, 10
	v_add_u32_e32 v2, v9, v2
	v_ashrrev_i16_sdwa v1, v6, sext(v1) dst_sel:DWORD dst_unused:UNUSED_PAD src0_sel:DWORD src1_sel:BYTE_0
	s_addc_u32 s26, s0, 0
	v_lshlrev_b32_e32 v4, 5, v8
	v_bfe_i32 v10, v1, 0, 16
	v_lshlrev_b32_e32 v1, 1, v2
	v_lshrrev_b32_e32 v3, 2, v2
	v_and_b32_e32 v5, 3, v9
	s_mov_b32 s0, 0x1fffe0
	v_and_b32_e32 v4, 32, v4
	v_and_b32_e32 v1, 24, v1
	v_and_b32_e32 v3, 4, v3
	v_and_or_b32 v5, v2, s0, v5
	v_or3_b32 v1, v5, v3, v1
	v_add_lshl_u32 v3, v4, v10, 1
	v_add_u32_e32 v0, 0x2000, v0
	v_lshl_add_u32 v188, v1, 11, v3
	v_ashrrev_i32_e32 v1, 31, v0
	v_lshrrev_b32_e32 v1, 22, v1
	v_add_u32_e32 v1, v0, v1
	s_waitcnt vmcnt(0)
	v_ashrrev_i32_e32 v12, 10, v1
	v_mul_i32_i24_e32 v1, 0x400, v12
	v_sub_u32_e32 v0, v0, v1
	v_lshrrev_b32_e32 v1, 4, v0
	v_bitop3_b32 v0, v1, v0, 32 bitop3:0x6c
	v_lshl_add_u32 v128, v2, 11, v3
	v_ashrrev_i32_e32 v2, 31, v0
	v_lshrrev_b32_e32 v2, 26, v2
	v_lshlrev_b32_e32 v1, 3, v12
	v_add_u32_e32 v2, v0, v2
	s_ashr_i32 s3, s4, 8
	v_and_b32_e32 v1, -16, v1
	v_ashrrev_i32_e32 v13, 6, v2
	v_add_u32_e32 v1, v13, v1
	v_and_b32_e32 v2, 0xc0, v2
	v_and_b32_e32 v4, 3, v13
	s_ashr_i32 s5, s4, 6
	s_ashr_i32 s15, s14, 31
	s_bfe_i64 s[6:7], s[2:3], 0x80000
	v_sub_u32_e32 v0, v0, v2
	v_and_or_b32 v4, v1, s0, v4
	s_lshl_b32 s27, s5, 10
	s_lshl_b64 s[0:1], s[14:15], 19
	s_lshl_b64 s[6:7], s[6:7], 19
	v_ashrrev_i16_sdwa v0, v6, sext(v0) dst_sel:DWORD dst_unused:UNUSED_PAD src0_sel:DWORD src1_sel:BYTE_0
	s_add_u32 s20, s25, s6
	v_lshlrev_b32_e32 v3, 5, v12
	v_bfe_i32 v14, v0, 0, 16
	v_lshlrev_b32_e32 v0, 1, v1
	v_lshrrev_b32_e32 v2, 2, v1
	s_addc_u32 s21, s26, s7
	s_add_i32 s28, s27, 0
	v_and_b32_e32 v3, 32, v3
	v_and_b32_e32 v0, 24, v0
	v_and_b32_e32 v2, 4, v2
	s_add_i32 m0, s28, 0x10000
	v_or3_b32 v0, v4, v2, v0
	v_add_lshl_u32 v2, v3, v14, 1
	s_mov_b64 exec, s[60:61]
	global_load_lds_dwordx4 v188, s[20:21]
	s_mov_b64 exec, -1
	s_add_i32 m0, s28, 0x12000
	v_lshl_add_u32 v132, v0, 11, v2
	s_add_u32 s6, s20, 0x40000
	s_mov_b64 exec, s[60:61]
	global_load_lds_dwordx4 v132, s[20:21]
	s_mov_b64 exec, -1
	s_addc_u32 s7, s21, 0
	s_add_i32 m0, s28, 0x14000
	v_lshl_add_u32 v130, v1, 11, v2
	s_mov_b64 exec, s[60:61]
	global_load_lds_dwordx4 v188, s[6:7]
	s_mov_b64 exec, -1
	s_add_i32 m0, s28, 0x16000
	v_mov_b32_e32 v133, v189
	s_mov_b64 exec, s[60:61]
	global_load_lds_dwordx4 v132, s[6:7]
	s_mov_b64 exec, -1
	v_readlane_b32 s6, v254, 19
	s_add_u32 s18, s6, s0
	v_readlane_b32 s0, v254, 20
	s_addc_u32 s19, s0, s1
	s_add_i32 s29, s28, 0x2000
	s_mov_b32 m0, s28
	s_add_u32 s0, s18, 0x40000
	s_mov_b64 exec, s[60:61]
	global_load_lds_dwordx4 v128, s[18:19]
	s_mov_b64 exec, -1
	s_mov_b32 m0, s29
	s_addc_u32 s1, s19, 0
	s_add_i32 s30, s28, 0x4000
	s_mov_b64 exec, s[60:61]
	global_load_lds_dwordx4 v130, s[18:19]
	s_mov_b64 exec, -1
	s_mov_b32 m0, s30
	s_add_i32 s31, s28, 0x6000
	s_mov_b64 exec, s[60:61]
	global_load_lds_dwordx4 v128, s[0:1]
	s_mov_b64 exec, -1
	s_mov_b32 m0, s31
	v_mov_b32_e32 v129, v189
	s_mov_b64 exec, s[60:61]
	global_load_lds_dwordx4 v130, s[0:1]
	s_mov_b64 exec, -1
	v_mov_b32_e32 v131, v189
	s_cmp_eq_u32 s3, 1
	v_lshl_add_u64 v[6:7], s[20:21], 0, v[188:189]
	v_lshl_add_u64 v[4:5], s[20:21], 0, v[132:133]
	v_lshl_add_u64 v[0:1], s[18:19], 0, v[128:129]
	s_cselect_b64 s[0:1], -1, 0
	s_cmp_lg_u32 s3, 1
	v_lshl_add_u64 v[2:3], s[18:19], 0, v[130:131]
	s_mov_b64 s[6:7], 0x80
	s_cbranch_scc1 .LBB0_717
	s_barrier
.LBB0_717:
	v_lshrrev_b32_e32 v16, 1, v11
	v_and_b32_e32 v16, 24, v16
	v_and_b32_e32 v15, 15, v11
	v_lshlrev_b32_e32 v17, 1, v16
	v_lshlrev_b32_e32 v11, 2, v11
	s_sext_i32_i8 s16, s2
	v_lshl_or_b32 v146, s3, 6, v15
	v_lshl_or_b32 v15, v15, 6, v17
	s_lshl_b32 s2, s3, 13
	v_and_b32_e32 v11, 32, v11
	v_bitop3_b32 v17, v15, s2, v11 bitop3:0xde
	s_lshl_b32 s2, s5, 5
	s_and_b32 s5, s2, 0x60
	s_add_i32 m0, s28, 0x18000
	v_lshl_add_u64 v[6:7], v[6:7], 0, s[6:7]
	s_lshl_b32 s2, s5, 7
	s_waitcnt vmcnt(2)
	s_barrier
	s_mov_b64 exec, s[60:61]
	global_load_lds_dwordx4 v[6:7], off
	s_mov_b64 exec, -1
	v_lshl_add_u64 v[4:5], v[4:5], 0, s[6:7]
	s_add_i32 m0, s28, 0x1a000
	s_add_i32 s34, s28, 0x8000
	s_add_i32 s35, s28, 0xa000
	v_bitop3_b32 v147, v15, s2, v11 bitop3:0xde
	s_mov_b64 exec, s[60:61]
	global_load_lds_dwordx4 v[4:5], off
	s_mov_b64 exec, -1
	v_lshl_add_u64 v[0:1], v[0:1], 0, s[6:7]
	s_mov_b32 m0, s34
	s_add_u32 s2, s20, 0x40080
	s_mov_b64 exec, s[60:61]
	global_load_lds_dwordx4 v[0:1], off
	s_mov_b64 exec, -1
	v_lshl_add_u64 v[0:1], v[2:3], 0, s[6:7]
	s_mov_b32 m0, s35
	s_addc_u32 s3, s21, 0
	s_mov_b64 exec, s[60:61]
	global_load_lds_dwordx4 v[0:1], off
	s_mov_b64 exec, -1
	s_add_i32 m0, s28, 0x1c000
	v_lshl_add_u64 v[0:1], s[2:3], 0, v[188:189]
	s_mov_b64 exec, s[60:61]
	global_load_lds_dwordx4 v[0:1], off
	s_mov_b64 exec, -1
	v_lshl_add_u64 v[0:1], s[2:3], 0, v[132:133]
	s_add_i32 m0, s28, 0x1e000
	s_cmpk_lt_u32 s4, 0x100
	s_mov_b64 exec, s[60:61]
	global_load_lds_dwordx4 v[0:1], off
	s_mov_b64 exec, -1
	v_lshlrev_b32_e32 v0, 14, v8
	v_and_b32_e32 v0, 0xffff8000, v0
	v_lshl_add_u32 v0, v9, 11, v0
	v_and_b32_e32 v1, 1, v8
	v_lshl_or_b32 v0, v1, 6, v0
	v_lshl_add_u32 v136, v10, 1, v0
	v_lshlrev_b32_e32 v0, 14, v12
	v_and_b32_e32 v0, 0xffff8000, v0
	s_waitcnt vmcnt(6)
	v_lshl_add_u32 v0, v13, 11, v0
	v_and_b32_e32 v1, 1, v12
	v_lshl_or_b32 v0, v1, 6, v0
	s_cselect_b64 s[2:3], -1, 0
	v_or_b32_e32 v134, s5, v16
	s_ashr_i32 s36, s24, 31
	v_mov_b32_e32 v137, v189
	v_lshl_add_u32 v138, v14, 1, v0
	v_mov_b32_e32 v139, v189
	s_mov_b32 s37, 0
	v_add_u32_e32 v148, 0, v17
	s_barrier
	s_branch .LBB0_720
